# attention hot blocks: packed f32 (v_pk_fma/v_pk_add) split into scalar f32 ops, bit-identical
# baseline (speedup 1.0000x reference)
; template <int MODE> ...
;     ...
; #pragma unroll
;     for (int tt = 0; tt < 2; ++tt)
; #pragma unroll
;       for (int hh = 0; hh < 2; ++hh) {
;         const float nb = nbias[tt][hh];
; #pragma unroll
;         for (int kh = 0; kh < 2; ++kh)
; #pragma unroll
;           for (int t = 0; t < 2; ++t) S[kh][tt][hh][t] = S[kh][tt][hh][t] * c1 + nb;
;       }
;     {
;       float mxq[2][2];
;       bool need = first;
; #pragma unroll
;       for (int tt = 0; tt < 2; ++tt)
; #pragma unroll
;         for (int hh = 0; hh < 2; ++hh) {
;           const float m0 = fmaxf(fmaxf(S[0][tt][hh][0][0], S[0][tt][hh][0][1]), S[0][tt][hh][0][2]);
;           const float m1 = fmaxf(fmaxf(S[0][tt][hh][1][0], S[0][tt][hh][1][1]), S[0][tt][hh][1][2]);
;           const float m2 = fmaxf(fmaxf(S[1][tt][hh][0][0], S[1][tt][hh][0][1]), S[1][tt][hh][0][2]);
;           const float m3 = fmaxf(fmaxf(S[1][tt][hh][1][0], S[1][tt][hh][1][1]), S[1][tt][hh][1][2]);
;           const float m4 = fmaxf(fmaxf(S[0][tt][hh][0][3], S[0][tt][hh][1][3]), m0);
;           const float m5 = fmaxf(fmaxf(S[1][tt][hh][0][3], S[1][tt][hh][1][3]), m1);
;           mxq[tt][hh] = fmaxf(fmaxf(m2, m3), fmaxf(m4, m5));
;           need = need || (mxq[tt][hh] > 8.f);
;         }
;       if (__builtin_amdgcn_ballot_w64(need) != 0) {
; #pragma unroll
;         for (int tt = 0; tt < 2; ++tt)
; #pragma unroll
;           for (int hh = 0; hh < 2; ++hh) {
;             float mx = mxq[tt][hh];
;             mx = fmaxf(mx, __shfl_xor(mx, 16));
;             mx = fmaxf(mx, __shfl_xor(mx, 32));
;             const float d = (mx == -INFINITY) ? 0.f : (first ? mx : fmaxf(mx, 0.f));
;             const float alpha = __builtin_amdgcn_exp2f(-d);
;             lsum[tt][hh] *= alpha;
;             nbias[tt][hh] -= d;
; #pragma unroll
;             for (int dt = 0; dt < 4; ++dt)
; #pragma unroll
;               for (int j = 0; j < 4; ++j) O[tt][hh][dt][j] *= alpha;
.LBB0_871:
	v_fma_f32 v196, v158, s28, v180
	v_fma_f32 v197, v159, s28, v180
	v_fma_f32 v198, v156, s28, v180
	v_fma_f32 v199, v157, s28, v180
	v_fma_f32 v190, v162, s28, v180
	v_fma_f32 v191, v163, s28, v180
	v_fma_f32 v192, v160, s28, v180
	v_fma_f32 v193, v161, s28, v180
	v_fma_f32 v170, v170, s28, v180
	v_fma_f32 v171, v171, s28, v180
	v_fma_f32 v166, v166, s28, v180
	v_fma_f32 v167, v167, s28, v180
	v_fma_f32 v200, v146, s28, v178
	v_fma_f32 v201, v147, s28, v178
	v_fma_f32 v146, v148, s28, v178
	v_fma_f32 v147, v149, s28, v178
	v_fma_f32 v148, v138, s28, v2
	v_fma_f32 v149, v139, s28, v2
	v_fma_f32 v138, v108, s28, v176
	v_fma_f32 v139, v109, s28, v176
	v_max3_f32 v109, v198, v199, v196
	v_fma_f32 v168, v168, s28, v180
	v_fma_f32 v169, v169, s28, v180
	v_fma_f32 v164, v164, s28, v180
	v_fma_f32 v165, v165, s28, v180
	v_fma_f32 v204, v142, s28, v178
	v_fma_f32 v205, v143, s28, v178
	v_fma_f32 v206, v140, s28, v178
	v_fma_f32 v207, v141, s28, v178
	v_fma_f32 v142, v152, s28, v178
	v_fma_f32 v143, v153, s28, v178
	v_fma_f32 v152, v134, s28, v2
	v_fma_f32 v153, v135, s28, v2
	v_fma_f32 v134, v112, s28, v176
	v_fma_f32 v135, v113, s28, v176
	v_max3_f32 v108, v192, v193, v190
	v_max_f32_e32 v112, v191, v197
	v_max3_f32 v109, v171, v167, v109
	v_fma_f32 v202, v144, s28, v178
	v_fma_f32 v203, v145, s28, v178
	v_fma_f32 v140, v154, s28, v178
	v_fma_f32 v141, v155, s28, v178
	v_fma_f32 v144, v150, s28, v178
	v_fma_f32 v145, v151, s28, v178
	v_fma_f32 v150, v136, s28, v2
	v_fma_f32 v151, v137, s28, v2
	v_fma_f32 v136, v110, s28, v176
	v_fma_f32 v137, v111, s28, v176
	v_max3_f32 v110, v168, v169, v170
	v_max3_f32 v111, v164, v165, v166
	v_max3_f32 v108, v112, v108, v109
	v_max3_f32 v109, v206, v207, v204
	v_fma_f32 v126, v126, s28, v2
	v_fma_f32 v127, v127, s28, v2
	v_fma_f32 v124, v124, s28, v2
	v_fma_f32 v125, v125, s28, v2
	v_max3_f32 v111, v110, v111, v108
	v_max3_f32 v108, v202, v203, v200
	v_max_f32_e32 v113, v201, v205
	v_max3_f32 v109, v141, v145, v109
	v_fma_f32 v130, v130, s28, v2
	v_fma_f32 v131, v131, s28, v2
	v_fma_f32 v128, v128, s28, v2
	v_fma_f32 v129, v129, s28, v2
	v_max3_f32 v110, v142, v143, v140
	v_max3_f32 v112, v146, v147, v144
	v_max3_f32 v108, v113, v108, v109
	v_max3_f32 v109, v124, v125, v126
	v_fma_f32 v154, v132, s28, v2
	v_fma_f32 v155, v133, s28, v2
	v_fma_f32 v132, v114, s28, v176
	v_fma_f32 v133, v115, s28, v176
	v_max3_f32 v110, v110, v112, v108
	v_max3_f32 v108, v128, v129, v130
	v_max_f32_e32 v114, v131, v127
	v_max3_f32 v109, v149, v153, v109
	v_max3_f32 v112, v150, v151, v148
	v_max3_f32 v113, v154, v155, v152
	v_max3_f32 v108, v114, v108, v109
	v_fma_f32 v156, v122, s28, v176
	v_fma_f32 v157, v123, s28, v176
	v_fma_f32 v160, v118, s28, v176
	v_fma_f32 v161, v119, s28, v176
	v_max3_f32 v109, v112, v113, v108
	v_max3_f32 v113, v138, v139, v136
	v_fma_f32 v158, v120, s28, v176
	v_fma_f32 v159, v121, s28, v176
	v_fma_f32 v162, v116, s28, v176
	v_fma_f32 v163, v117, s28, v176
	v_max3_f32 v108, v134, v135, v132
	v_max_f32_e32 v116, v133, v137
	v_max3_f32 v113, v157, v161, v113
	v_max3_f32 v114, v158, v159, v156
	v_max3_f32 v115, v162, v163, v160
	v_max3_f32 v108, v116, v108, v113
	v_max3_f32 v112, v109, v110, v111
	v_max3_f32 v108, v114, v115, v108
	v_max_f32_e32 v112, v108, v112
	s_mov_b32 s23, 0x41000000
	v_cmp_lt_f32_e32 vcc, s23, v112
	s_or_b64 s[58:59], s[42:43], vcc
	v_cndmask_b32_e64 v112, 0, 1, s[58:59]
	v_cmp_ne_u32_e32 vcc, 0, v112
	s_cbranch_vccz .LBB0_873
	v_and_b32_e32 v113, 64, v226
	v_xor_b32_e32 v112, 16, v226
	v_add_u32_e32 v113, 64, v113
	v_cmp_lt_i32_e32 vcc, v112, v113
	s_nop 1
	v_cndmask_b32_e32 v112, v226, v112, vcc
	v_lshlrev_b32_e32 v114, 2, v112
	v_xor_b32_e32 v112, 32, v226
	v_cmp_lt_i32_e32 vcc, v112, v113
	s_nop 1
	v_cndmask_b32_e32 v112, v226, v112, vcc
	v_lshlrev_b32_e32 v115, 2, v112
	ds_bpermute_b32 v112, v114, v111
	v_max_f32_e32 v111, v111, v111
	s_waitcnt lgkmcnt(0)
	v_max_f32_e32 v112, v112, v112
	v_max_f32_e32 v111, v111, v112
	ds_bpermute_b32 v112, v115, v111
	s_waitcnt lgkmcnt(0)
	v_max_f32_e32 v112, v112, v112
	v_max_f32_e32 v111, v111, v112
	v_max_f32_e32 v112, 0, v111
	v_cndmask_b32_e64 v112, v112, v111, s[42:43]
	v_cmp_neq_f32_e32 vcc, s20, v111
	s_nop 1
	v_cndmask_b32_e32 v111, 0, v112, vcc
	v_exp_f32_e64 v112, -v111
	v_sub_f32_e32 v180, v180, v111
	v_sub_f32_e32 v192, v192, v111
	v_sub_f32_e32 v193, v193, v111
	v_sub_f32_e32 v190, v190, v111
	v_sub_f32_e32 v191, v191, v111
	v_sub_f32_e32 v198, v198, v111
	v_sub_f32_e32 v199, v199, v111
	v_sub_f32_e32 v196, v196, v111
	v_sub_f32_e32 v197, v197, v111
	v_sub_f32_e32 v168, v168, v111
	v_sub_f32_e32 v169, v169, v111
	v_sub_f32_e32 v170, v170, v111
	v_sub_f32_e32 v171, v171, v111
	v_sub_f32_e32 v164, v164, v111
	v_sub_f32_e32 v165, v165, v111
	v_sub_f32_e32 v166, v166, v111
	v_sub_f32_e32 v167, v167, v111
	ds_bpermute_b32 v111, v114, v110
	v_max_f32_e32 v110, v110, v110
	v_pk_mul_f32 v[54:55], v[54:55], v[112:113] op_sel_hi:[1,0]
	v_pk_mul_f32 v[52:53], v[52:53], v[112:113] op_sel_hi:[1,0]
	v_pk_mul_f32 v[62:63], v[62:63], v[112:113] op_sel_hi:[1,0]
	s_waitcnt lgkmcnt(0)
	v_max_f32_e32 v111, v111, v111
	v_max_f32_e32 v110, v110, v111
	ds_bpermute_b32 v111, v115, v110
	v_pk_mul_f32 v[60:61], v[60:61], v[112:113] op_sel_hi:[1,0]
	v_pk_mul_f32 v[58:59], v[58:59], v[112:113] op_sel_hi:[1,0]
	v_pk_mul_f32 v[56:57], v[56:57], v[112:113] op_sel_hi:[1,0]
	v_pk_mul_f32 v[66:67], v[66:67], v[112:113] op_sel_hi:[1,0]
	s_waitcnt lgkmcnt(0)
; template <int MODE> ...
;     ...
; #pragma unroll
;         for (int tt = 0; tt < 2; ++tt)
; #pragma unroll
;           for (int hh = 0; hh < 2; ++hh) {
;             float mx = mxq[tt][hh];
;             mx = fmaxf(mx, __shfl_xor(mx, 16));
;             mx = fmaxf(mx, __shfl_xor(mx, 32));
;             const float d = (mx == -INFINITY) ? 0.f : (first ? mx : fmaxf(mx, 0.f));
;             const float alpha = __builtin_amdgcn_exp2f(-d);
;             lsum[tt][hh] *= alpha;
;             nbias[tt][hh] -= d;
; #pragma unroll
;             for (int dt = 0; dt < 4; ++dt)
; #pragma unroll
;               for (int j = 0; j < 4; ++j) O[tt][hh][dt][j] *= alpha;
; #pragma unroll
;             for (int kh = 0; kh < 2; ++kh)
; #pragma unroll
;               for (int t = 0; t < 2; ++t) S[kh][tt][hh][t] = S[kh][tt][hh][t] - d;
;           }
	v_max_f32_e32 v111, v111, v111
	v_max_f32_e32 v110, v110, v111
	v_max_f32_e32 v111, 0, v110
	v_cndmask_b32_e64 v111, v111, v110, s[42:43]
	v_cmp_neq_f32_e32 vcc, s20, v110
	v_pk_mul_f32 v[64:65], v[64:65], v[112:113] op_sel_hi:[1,0]
	s_nop 0
	v_cndmask_b32_e32 v111, 0, v111, vcc
	v_exp_f32_e64 v113, -v111
	v_sub_f32_e32 v178, v178, v111
	v_sub_f32_e32 v202, v202, v111
	v_sub_f32_e32 v203, v203, v111
	v_mov_b32_e32 v110, v113
	v_pk_mul_f32 v[46:47], v[46:47], v[110:111] op_sel_hi:[1,0]
	v_pk_mul_f32 v[44:45], v[44:45], v[110:111] op_sel_hi:[1,0]
	v_pk_mul_f32 v[42:43], v[42:43], v[110:111] op_sel_hi:[1,0]
	v_pk_mul_f32 v[40:41], v[40:41], v[110:111] op_sel_hi:[1,0]
	v_pk_mul_f32 v[38:39], v[38:39], v[110:111] op_sel_hi:[1,0]
	v_pk_mul_f32 v[36:37], v[36:37], v[110:111] op_sel_hi:[1,0]
	v_pk_mul_f32 v[50:51], v[50:51], v[110:111] op_sel_hi:[1,0]
	v_pk_mul_f32 v[48:49], v[48:49], v[110:111] op_sel_hi:[1,0]
	ds_bpermute_b32 v110, v114, v109
	v_max_f32_e32 v109, v109, v109
	v_sub_f32_e32 v200, v200, v111
	v_sub_f32_e32 v201, v201, v111
	v_sub_f32_e32 v206, v206, v111
	s_waitcnt lgkmcnt(0)
	v_max_f32_e32 v110, v110, v110
	v_max_f32_e32 v109, v109, v110
	ds_bpermute_b32 v110, v115, v109
	v_sub_f32_e32 v207, v207, v111
	v_sub_f32_e32 v204, v204, v111
	v_sub_f32_e32 v205, v205, v111
	v_sub_f32_e32 v142, v142, v111
	s_waitcnt lgkmcnt(0)
	v_max_f32_e32 v110, v110, v110
	v_max_f32_e32 v109, v109, v110
	v_max_f32_e32 v110, 0, v109
	v_cndmask_b32_e64 v110, v110, v109, s[42:43]
	v_cmp_neq_f32_e32 vcc, s20, v109
	v_sub_f32_e32 v143, v143, v111
	v_sub_f32_e32 v140, v140, v111
	v_cndmask_b32_e32 v109, 0, v110, vcc
	v_exp_f32_e64 v110, -v109
	v_sub_f32_e32 v2, v2, v109
	v_sub_f32_e32 v128, v128, v109
	v_sub_f32_e32 v129, v129, v109
	v_sub_f32_e32 v130, v130, v109
	v_sub_f32_e32 v131, v131, v109
	v_sub_f32_e32 v124, v124, v109
	v_sub_f32_e32 v125, v125, v109
	v_sub_f32_e32 v126, v126, v109
	v_sub_f32_e32 v127, v127, v109
	v_sub_f32_e32 v150, v150, v109
	v_sub_f32_e32 v151, v151, v109
	v_sub_f32_e32 v148, v148, v109
	v_sub_f32_e32 v149, v149, v109
	v_sub_f32_e32 v154, v154, v109
	v_sub_f32_e32 v155, v155, v109
	v_sub_f32_e32 v152, v152, v109
	v_sub_f32_e32 v153, v153, v109
	ds_bpermute_b32 v109, v114, v108
	v_max_f32_e32 v108, v108, v108
	v_sub_f32_e32 v141, v141, v111
	v_sub_f32_e32 v146, v146, v111
	v_sub_f32_e32 v147, v147, v111
	s_waitcnt lgkmcnt(0)
	v_max_f32_e32 v109, v109, v109
	v_max_f32_e32 v108, v108, v109
	ds_bpermute_b32 v109, v115, v108
	v_sub_f32_e32 v144, v144, v111
	v_sub_f32_e32 v145, v145, v111
	v_pk_mul_f32 v[34:35], v[34:35], v[110:111] op_sel_hi:[1,0]
	v_pk_mul_f32 v[32:33], v[32:33], v[110:111] op_sel_hi:[1,0]
	s_waitcnt lgkmcnt(0)
	v_max_f32_e32 v109, v109, v109
	v_max_f32_e32 v108, v108, v109
	v_max_f32_e32 v109, 0, v108
	v_cndmask_b32_e64 v109, v109, v108, s[42:43]
	v_cmp_neq_f32_e32 vcc, s20, v108
	v_pk_mul_f32 v[30:31], v[30:31], v[110:111] op_sel_hi:[1,0]
	v_pk_mul_f32 v[28:29], v[28:29], v[110:111] op_sel_hi:[1,0]
	v_cndmask_b32_e32 v109, 0, v109, vcc
	v_pk_mul_f32 v[26:27], v[26:27], v[110:111] op_sel_hi:[1,0]
	v_pk_mul_f32 v[24:25], v[24:25], v[110:111] op_sel_hi:[1,0]
	v_pk_mul_f32 v[22:23], v[22:23], v[110:111] op_sel_hi:[1,0]
	v_pk_mul_f32 v[20:21], v[20:21], v[110:111] op_sel_hi:[1,0]
	v_exp_f32_e64 v111, -v109
	v_pk_mul_f32 v[188:189], v[188:189], v[112:113]
	v_sub_f32_e32 v176, v176, v109
	v_sub_f32_e32 v134, v134, v109
	v_mov_b32_e32 v108, v111
	v_pk_mul_f32 v[186:187], v[186:187], v[110:111]
	v_pk_mul_f32 v[18:19], v[18:19], v[108:109] op_sel_hi:[1,0]
	v_pk_mul_f32 v[16:17], v[16:17], v[108:109] op_sel_hi:[1,0]
	v_pk_mul_f32 v[14:15], v[14:15], v[108:109] op_sel_hi:[1,0]
	v_pk_mul_f32 v[12:13], v[12:13], v[108:109] op_sel_hi:[1,0]
	v_pk_mul_f32 v[10:11], v[10:11], v[108:109] op_sel_hi:[1,0]
	v_pk_mul_f32 v[8:9], v[8:9], v[108:109] op_sel_hi:[1,0]
	v_pk_mul_f32 v[6:7], v[6:7], v[108:109] op_sel_hi:[1,0]
	v_pk_mul_f32 v[4:5], v[4:5], v[108:109] op_sel_hi:[1,0]
	v_sub_f32_e32 v135, v135, v109
	v_sub_f32_e32 v132, v132, v109
	v_sub_f32_e32 v133, v133, v109
	v_sub_f32_e32 v138, v138, v109
	v_sub_f32_e32 v139, v139, v109
	v_sub_f32_e32 v136, v136, v109
	v_sub_f32_e32 v137, v137, v109
	v_sub_f32_e32 v158, v158, v109
	v_sub_f32_e32 v159, v159, v109
	v_sub_f32_e32 v156, v156, v109
	v_sub_f32_e32 v157, v157, v109
	v_sub_f32_e32 v162, v162, v109
	v_sub_f32_e32 v163, v163, v109
	v_sub_f32_e32 v160, v160, v109
	v_sub_f32_e32 v161, v161, v109
; #define MFMA(a, b, c) __builtin_amdgcn_mfma_f32_16x16x32_bf16((a), (b), (c), 0, 0, 0)
; template <int MODE> ...
;     ...
; #pragma unroll
;     for (int kh = 0; kh < 2; ++kh) {
; #pragma unroll
;       for (int tt = 0; tt < 2; ++tt) {
;         bf16x8 pf[2];
; #pragma unroll
;         for (int hh = 0; hh < 2; ++hh) {
;           float pv[8];
; #pragma unroll
;           for (int j = 0; j < 4; ++j) {
;             pv[j] = __builtin_amdgcn_exp2f(S[kh][tt][hh][0][j]);
;             pv[4 + j] = __builtin_amdgcn_exp2f(S[kh][tt][hh][1][j]);
;           }
;           lsum[tt][hh] += ((pv[0] + pv[1]) + (pv[2] + pv[3])) + ((pv[4] + pv[5]) + (pv[6] + pv[7]));
;           const uint4 pk = make_uint4(pack2(pv[0], pv[1]), pack2(pv[2], pv[3]), pack2(pv[4], pv[5]), pack2(pv[6], pv[7]));
;           pf[hh] = __builtin_bit_cast(bf16x8, pk);
;         }
; #pragma unroll
;         for (int dt = 0; dt < 4; ++dt) {
;           const bf16x8 vf = *(const bf16x8*)&Vs[(dt * 16 + r) * 64 + (((kh * 4 + g) ^ (r & 7)) * 8)];
;           O[tt][0][dt] = MFMA(vf, pf[0], O[tt][0][dt]);
;           O[tt][1][dt] = MFMA(vf, pf[1], O[tt][1][dt]);
;         }
;       }
;     }
;     }
;     if (more) {
;       u16* Kn = Kbase + ((it + 1) & 1) * (2 * 64 * 64);
;       *(uint4*)&Kn[kwoff] = kr0;
;       *(uint4*)&Kn[64 * 64 + vwoff] = vr0;
;     }
.LBB0_873:
	ds_read_b128 v[120:123], v234 offset:8192
	ds_read_b128 v[116:119], v234 offset:10240
	ds_read_b128 v[112:115], v234 offset:12288
	ds_read_b128 v[108:111], v234 offset:14336
	v_exp_f32_e32 v208, v192
	v_exp_f32_e32 v212, v193
	v_exp_f32_e32 v216, v190
	v_exp_f32_e32 v220, v191
	v_exp_f32_e32 v209, v202
	v_exp_f32_e32 v213, v203
	v_exp_f32_e32 v217, v200
	v_exp_f32_e32 v221, v201
	v_exp_f32_e32 v210, v198
	v_exp_f32_e32 v214, v199
	v_exp_f32_e32 v218, v196
	v_exp_f32_e32 v222, v197
	v_exp_f32_e32 v211, v206
	v_exp_f32_e32 v215, v207
	v_exp_f32_e32 v219, v204
	v_exp_f32_e32 v223, v205
	v_add_f32_e32 v248, v212, v208
	v_add_f32_e32 v249, v213, v209
	v_add_f32_e32 v250, v220, v216
	v_add_f32_e32 v251, v221, v217
	v_add_f32_e32 v248, v250, v248
	v_add_f32_e32 v249, v251, v249
	v_add_f32_e32 v250, v214, v210
	v_add_f32_e32 v251, v215, v211
	v_add_f32_e32 v252, v222, v218
	v_add_f32_e32 v253, v223, v219
	v_add_f32_e32 v250, v252, v250
	v_add_f32_e32 v251, v253, v251
	v_add_f32_e32 v248, v250, v248
	v_add_f32_e32 v249, v251, v249
	v_add_f32_e32 v188, v248, v188
	v_add_f32_e32 v189, v249, v189
	v_cvt_pk_bf16_f32 v240, v208, v212
	v_cvt_pk_bf16_f32 v241, v216, v220
	v_cvt_pk_bf16_f32 v242, v210, v214
	v_cvt_pk_bf16_f32 v243, v218, v222
	v_cvt_pk_bf16_f32 v244, v209, v213
	v_cvt_pk_bf16_f32 v245, v217, v221
	v_cvt_pk_bf16_f32 v246, v211, v215
	v_cvt_pk_bf16_f32 v247, v219, v223
	ds_read_b128 v[208:211], v0 offset:8192
	ds_read_b128 v[212:215], v0 offset:10240
	ds_read_b128 v[216:219], v0 offset:12288
	ds_read_b128 v[220:223], v0 offset:14336
	s_mov_b64 s[42:43], 0
	s_waitcnt lgkmcnt(4)
	v_mfma_f32_16x16x32_bf16 v[52:55], v[120:123], v[240:243], v[52:55]
	v_exp_f32_e32 v200, v129
	v_mfma_f32_16x16x32_bf16 v[60:63], v[116:119], v[240:243], v[60:63]
	v_exp_f32_e32 v196, v125
	v_mfma_f32_16x16x32_bf16 v[56:59], v[112:115], v[240:243], v[56:59]
	v_exp_f32_e32 v198, v126
	v_mfma_f32_16x16x32_bf16 v[64:67], v[108:111], v[240:243], v[64:67]
	v_exp_f32_e32 v206, v131
	v_mfma_f32_16x16x32_bf16 v[44:47], v[120:123], v[244:247], v[44:47]
	v_exp_f32_e32 v204, v127
	v_mfma_f32_16x16x32_bf16 v[40:43], v[116:119], v[244:247], v[40:43]
	v_exp_f32_e32 v193, v134
	v_mfma_f32_16x16x32_bf16 v[36:39], v[112:115], v[244:247], v[36:39]
	v_exp_f32_e32 v191, v138
	v_mfma_f32_16x16x32_bf16 v[48:51], v[108:111], v[244:247], v[48:51]
	v_exp_f32_e32 v201, v135
	v_exp_f32_e32 v197, v139
	v_exp_f32_e32 v203, v132
	v_exp_f32_e32 v207, v133
	v_exp_f32_e32 v205, v137
	v_exp_f32_e32 v192, v128
	v_exp_f32_e32 v190, v124
	v_exp_f32_e32 v202, v130
	v_exp_f32_e32 v199, v136
	v_add_f32_e32 v248, v200, v192
	v_add_f32_e32 v249, v201, v193
	v_add_f32_e32 v250, v206, v202
	v_add_f32_e32 v251, v207, v203
	v_add_f32_e32 v248, v250, v248
	v_add_f32_e32 v249, v251, v249
	v_add_f32_e32 v250, v196, v190
	v_add_f32_e32 v251, v197, v191
	v_add_f32_e32 v252, v204, v198
	v_add_f32_e32 v253, v205, v199
	v_add_f32_e32 v250, v252, v250
	v_add_f32_e32 v251, v253, v251
	v_add_f32_e32 v248, v250, v248
	v_add_f32_e32 v249, v251, v249
	v_add_f32_e32 v186, v248, v186
	v_add_f32_e32 v187, v249, v187
	v_cvt_pk_bf16_f32 v240, v192, v200
	v_cvt_pk_bf16_f32 v241, v202, v206
	v_cvt_pk_bf16_f32 v242, v190, v196
	v_cvt_pk_bf16_f32 v243, v198, v204
	v_cvt_pk_bf16_f32 v244, v193, v201
	v_cvt_pk_bf16_f32 v245, v203, v207
	v_cvt_pk_bf16_f32 v246, v191, v197
	v_cvt_pk_bf16_f32 v247, v199, v205
	v_mfma_f32_16x16x32_bf16 v[20:23], v[108:111], v[240:243], v[20:23]
	v_exp_f32_e32 v126, v168
	v_mfma_f32_16x16x32_bf16 v[32:35], v[120:123], v[240:243], v[32:35]
	v_exp_f32_e32 v132, v169
	v_mfma_f32_16x16x32_bf16 v[28:31], v[116:119], v[240:243], v[28:31]
	v_exp_f32_e32 v134, v170
	v_mfma_f32_16x16x32_bf16 v[24:27], v[112:115], v[240:243], v[24:27]
	v_exp_f32_e32 v138, v171
	v_mfma_f32_16x16x32_bf16 v[4:7], v[108:111], v[244:247], v[4:7]
	v_exp_f32_e32 v127, v142
	v_mfma_f32_16x16x32_bf16 v[16:19], v[120:123], v[244:247], v[16:19]
	v_exp_f32_e32 v125, v146
	v_mfma_f32_16x16x32_bf16 v[12:15], v[116:119], v[244:247], v[12:15]
	v_exp_f32_e32 v133, v143
	v_mfma_f32_16x16x32_bf16 v[8:11], v[112:115], v[244:247], v[8:11]
	v_exp_f32_e32 v129, v147
	s_andn2_b64 vcc, exec, s[56:57]
	s_cbranch_vccnz .Lattn1_nw
	s_and_b32 s98, s2, 0x2000
	s_lshl_b32 s98, s98, 1
	s_add_i32 s98, s98, 32
	v_lshl_add_u32 v235, v3, 1, s98
	v_lshl_add_u32 v238, v229, 1, s98
	s_waitcnt vmcnt(1)
	ds_write_b128 v235, v[100:103]
	s_waitcnt vmcnt(0)
	ds_write_b128 v238, v[104:107] offset:8192
; #define MFMA(a, b, c) __builtin_amdgcn_mfma_f32_16x16x32_bf16((a), (b), (c), 0, 0, 0)
; template <int MODE> ...
;     ...
; #pragma unroll
;     for (int kh = 0; kh < 2; ++kh) {
; #pragma unroll
;       for (int tt = 0; tt < 2; ++tt) {
;         bf16x8 pf[2];
; #pragma unroll
;         for (int hh = 0; hh < 2; ++hh) {
;           float pv[8];
; #pragma unroll
;           for (int j = 0; j < 4; ++j) {
;             pv[j] = __builtin_amdgcn_exp2f(S[kh][tt][hh][0][j]);
;             pv[4 + j] = __builtin_amdgcn_exp2f(S[kh][tt][hh][1][j]);
;           }
;           lsum[tt][hh] += ((pv[0] + pv[1]) + (pv[2] + pv[3])) + ((pv[4] + pv[5]) + (pv[6] + pv[7]));
;           const uint4 pk = make_uint4(pack2(pv[0], pv[1]), pack2(pv[2], pv[3]), pack2(pv[4], pv[5]), pack2(pv[6], pv[7]));
;           pf[hh] = __builtin_bit_cast(bf16x8, pk);
;         }
; #pragma unroll
;         for (int dt = 0; dt < 4; ++dt) {
;           const bf16x8 vf = *(const bf16x8*)&Vs[(dt * 16 + r) * 64 + (((kh * 4 + g) ^ (r & 7)) * 8)];
;           O[tt][0][dt] = MFMA(vf, pf[0], O[tt][0][dt]);
;           O[tt][1][dt] = MFMA(vf, pf[1], O[tt][1][dt]);
;         }
;       }
;     }
.Lattn1_nw:
	v_exp_f32_e32 v135, v140
	v_exp_f32_e32 v131, v144
	v_exp_f32_e32 v139, v141
	v_exp_f32_e32 v137, v145
	v_exp_f32_e32 v124, v164
	v_exp_f32_e32 v128, v165
	v_exp_f32_e32 v130, v166
	v_exp_f32_e32 v136, v167
	v_add_f32_e32 v248, v132, v126
	v_add_f32_e32 v249, v133, v127
	v_add_f32_e32 v250, v138, v134
	v_add_f32_e32 v251, v139, v135
	v_add_f32_e32 v248, v250, v248
	v_add_f32_e32 v249, v251, v249
	v_add_f32_e32 v250, v128, v124
	v_add_f32_e32 v251, v129, v125
	v_add_f32_e32 v252, v136, v130
	v_add_f32_e32 v253, v137, v131
	v_add_f32_e32 v250, v252, v250
	v_add_f32_e32 v251, v253, v251
	v_add_f32_e32 v248, v250, v248
	v_add_f32_e32 v249, v251, v249
	v_add_f32_e32 v188, v248, v188
	v_add_f32_e32 v189, v249, v189
	v_cvt_pk_bf16_f32 v240, v126, v132
	v_cvt_pk_bf16_f32 v241, v134, v138
	v_cvt_pk_bf16_f32 v242, v124, v128
	v_cvt_pk_bf16_f32 v243, v130, v136
	v_cvt_pk_bf16_f32 v244, v127, v133
	v_cvt_pk_bf16_f32 v245, v135, v139
	v_cvt_pk_bf16_f32 v246, v125, v129
	v_cvt_pk_bf16_f32 v247, v131, v137
	s_waitcnt lgkmcnt(0)
	v_mfma_f32_16x16x32_bf16 v[52:55], v[208:211], v[240:243], v[52:55]
	v_exp_f32_e32 v148, v148
	v_mfma_f32_16x16x32_bf16 v[60:63], v[212:215], v[240:243], v[60:63]
	v_exp_f32_e32 v146, v152
	v_mfma_f32_16x16x32_bf16 v[56:59], v[216:219], v[240:243], v[56:59]
	v_exp_f32_e32 v152, v153
	v_mfma_f32_16x16x32_bf16 v[64:67], v[220:223], v[240:243], v[64:67]
	v_exp_f32_e32 v145, v163
	v_mfma_f32_16x16x32_bf16 v[44:47], v[208:211], v[244:247], v[44:47]
	v_exp_f32_e32 v141, v162
	v_mfma_f32_16x16x32_bf16 v[40:43], v[212:215], v[244:247], v[40:43]
	v_exp_f32_e32 v147, v160
	v_mfma_f32_16x16x32_bf16 v[36:39], v[216:219], v[244:247], v[36:39]
	v_exp_f32_e32 v153, v161
	v_mfma_f32_16x16x32_bf16 v[48:51], v[220:223], v[244:247], v[48:51]
	v_exp_f32_e32 v142, v150
	v_exp_f32_e32 v140, v154
	v_exp_f32_e32 v150, v151
	v_exp_f32_e32 v144, v155
	v_exp_f32_e32 v154, v149
	v_exp_f32_e32 v143, v158
	v_exp_f32_e32 v151, v159
	v_exp_f32_e32 v149, v156
	v_exp_f32_e32 v155, v157
	v_add_f32_e32 v248, v150, v142
	v_add_f32_e32 v249, v151, v143
	v_add_f32_e32 v250, v154, v148
	v_add_f32_e32 v251, v155, v149
	v_add_f32_e32 v248, v250, v248
	v_add_f32_e32 v249, v251, v249
	v_add_f32_e32 v250, v144, v140
	v_add_f32_e32 v251, v145, v141
	v_add_f32_e32 v252, v152, v146
	v_add_f32_e32 v253, v153, v147
	v_add_f32_e32 v250, v252, v250
	v_add_f32_e32 v251, v253, v251
	v_add_f32_e32 v248, v250, v248
	v_add_f32_e32 v249, v251, v249
	v_add_f32_e32 v186, v248, v186
	v_add_f32_e32 v187, v249, v187
	v_cvt_pk_bf16_f32 v240, v142, v150
	v_cvt_pk_bf16_f32 v241, v148, v154
	v_cvt_pk_bf16_f32 v242, v140, v144
	v_cvt_pk_bf16_f32 v243, v146, v152
	v_cvt_pk_bf16_f32 v244, v143, v151
	v_cvt_pk_bf16_f32 v245, v149, v155
	v_cvt_pk_bf16_f32 v246, v141, v145
	v_cvt_pk_bf16_f32 v247, v147, v153
	v_mfma_f32_16x16x32_bf16 v[32:35], v[208:211], v[240:243], v[32:35]
	v_mfma_f32_16x16x32_bf16 v[28:31], v[212:215], v[240:243], v[28:31]
	v_mfma_f32_16x16x32_bf16 v[24:27], v[216:219], v[240:243], v[24:27]
	v_mfma_f32_16x16x32_bf16 v[20:23], v[220:223], v[240:243], v[20:23]
	v_mfma_f32_16x16x32_bf16 v[16:19], v[208:211], v[244:247], v[16:19]
	v_mfma_f32_16x16x32_bf16 v[12:15], v[212:215], v[244:247], v[12:15]
	v_mfma_f32_16x16x32_bf16 v[8:11], v[216:219], v[244:247], v[8:11]
	v_mfma_f32_16x16x32_bf16 v[4:7], v[220:223], v[244:247], v[4:7]
	s_andn2_b64 vcc, exec, s[56:57]
	s_cbranch_vccz .Lattn1_adv

; template <int MODE> ...
;     ...
; #pragma unroll
;     for (int tt = 0; tt < 2; ++tt)
; #pragma unroll
;       for (int hh = 0; hh < 2; ++hh) {
;         const float nb = nbias[tt][hh];
; #pragma unroll
;         for (int kh = 0; kh < 2; ++kh)
; #pragma unroll
;           for (int t = 0; t < 2; ++t) S[kh][tt][hh][t] = S[kh][tt][hh][t] * c1 + nb;
;       }
;     {
;       float mxq[2][2];
;       bool need = first;
; #pragma unroll
;       for (int tt = 0; tt < 2; ++tt)
; #pragma unroll
;         for (int hh = 0; hh < 2; ++hh) {
;           const float m0 = fmaxf(fmaxf(S[0][tt][hh][0][0], S[0][tt][hh][0][1]), S[0][tt][hh][0][2]);
;           const float m1 = fmaxf(fmaxf(S[0][tt][hh][1][0], S[0][tt][hh][1][1]), S[0][tt][hh][1][2]);
;           const float m2 = fmaxf(fmaxf(S[1][tt][hh][0][0], S[1][tt][hh][0][1]), S[1][tt][hh][0][2]);
;           const float m3 = fmaxf(fmaxf(S[1][tt][hh][1][0], S[1][tt][hh][1][1]), S[1][tt][hh][1][2]);
;           const float m4 = fmaxf(fmaxf(S[0][tt][hh][0][3], S[0][tt][hh][1][3]), m0);
;           const float m5 = fmaxf(fmaxf(S[1][tt][hh][0][3], S[1][tt][hh][1][3]), m1);
;           mxq[tt][hh] = fmaxf(fmaxf(m2, m3), fmaxf(m4, m5));
;           need = need || (mxq[tt][hh] > 8.f);
;         }
;       if (__builtin_amdgcn_ballot_w64(need) != 0) {
; #pragma unroll
;         for (int tt = 0; tt < 2; ++tt)
; #pragma unroll
;           for (int hh = 0; hh < 2; ++hh) {
;             float mx = mxq[tt][hh];
;             mx = fmaxf(mx, __shfl_xor(mx, 16));
;             mx = fmaxf(mx, __shfl_xor(mx, 32));
;             const float d = (mx == -INFINITY) ? 0.f : (first ? mx : fmaxf(mx, 0.f));
;             const float alpha = __builtin_amdgcn_exp2f(-d);
;             lsum[tt][hh] *= alpha;
;             nbias[tt][hh] -= d;
; #pragma unroll
;             for (int dt = 0; dt < 4; ++dt)
; #pragma unroll
;               for (int j = 0; j < 4; ++j) O[tt][hh][dt][j] *= alpha;
.LBB0_891:
	v_fma_f32 v178, v140, s36, v162
	v_fma_f32 v179, v141, s36, v162
	v_fma_f32 v180, v138, s36, v162
	v_fma_f32 v181, v139, s36, v162
	v_fma_f32 v174, v144, s36, v162
	v_fma_f32 v175, v145, s36, v162
	v_fma_f32 v176, v142, s36, v162
	v_fma_f32 v177, v143, s36, v162
	v_fma_f32 v152, v152, s36, v162
	v_fma_f32 v153, v153, s36, v162
	v_fma_f32 v148, v148, s36, v162
	v_fma_f32 v149, v149, s36, v162
	v_fma_f32 v182, v128, s36, v164
	v_fma_f32 v183, v129, s36, v164
	v_fma_f32 v128, v130, s36, v164
	v_fma_f32 v129, v131, s36, v164
	v_fma_f32 v130, v120, s36, v160
	v_fma_f32 v131, v121, s36, v160
	v_fma_f32 v120, v90, s36, v158
	v_fma_f32 v121, v91, s36, v158
	v_max3_f32 v91, v180, v181, v178
	v_fma_f32 v150, v150, s36, v162
	v_fma_f32 v151, v151, s36, v162
	v_fma_f32 v146, v146, s36, v162
	v_fma_f32 v147, v147, s36, v162
	v_fma_f32 v186, v124, s36, v164
	v_fma_f32 v187, v125, s36, v164
	v_fma_f32 v188, v122, s36, v164
	v_fma_f32 v189, v123, s36, v164
	v_fma_f32 v124, v134, s36, v164
	v_fma_f32 v125, v135, s36, v164
	v_fma_f32 v134, v112, s36, v160
	v_fma_f32 v135, v113, s36, v160
	v_fma_f32 v112, v94, s36, v158
	v_fma_f32 v113, v95, s36, v158
	v_max3_f32 v90, v176, v177, v174
	v_max_f32_e32 v94, v175, v179
	v_max3_f32 v91, v153, v149, v91
	v_fma_f32 v184, v126, s36, v164
	v_fma_f32 v185, v127, s36, v164
	v_fma_f32 v122, v136, s36, v164
	v_fma_f32 v123, v137, s36, v164
	v_fma_f32 v126, v132, s36, v164
	v_fma_f32 v127, v133, s36, v164
	v_fma_f32 v132, v118, s36, v160
	v_fma_f32 v133, v119, s36, v160
	v_fma_f32 v118, v92, s36, v158
	v_fma_f32 v119, v93, s36, v158
	v_max3_f32 v92, v150, v151, v152
	v_max3_f32 v93, v146, v147, v148
	v_max3_f32 v90, v94, v90, v91
	v_max3_f32 v91, v188, v189, v186
	v_fma_f32 v108, v108, s36, v160
	v_fma_f32 v109, v109, s36, v160
	v_fma_f32 v106, v106, s36, v160
	v_fma_f32 v107, v107, s36, v160
	v_max3_f32 v93, v92, v93, v90
	v_max3_f32 v90, v184, v185, v182
	v_max_f32_e32 v95, v183, v187
	v_max3_f32 v91, v123, v127, v91
	v_fma_f32 v116, v116, s36, v160
	v_fma_f32 v117, v117, s36, v160
	v_fma_f32 v114, v114, s36, v160
	v_fma_f32 v115, v115, s36, v160
	v_max3_f32 v92, v124, v125, v122
	v_max3_f32 v94, v128, v129, v126
	v_max3_f32 v90, v95, v90, v91
	v_max3_f32 v91, v106, v107, v108
	v_fma_f32 v136, v110, s36, v160
	v_fma_f32 v137, v111, s36, v160
	v_fma_f32 v110, v96, s36, v158
	v_fma_f32 v111, v97, s36, v158
	v_max3_f32 v92, v92, v94, v90
	v_max3_f32 v90, v114, v115, v116
	v_max_f32_e32 v96, v117, v109
	v_max3_f32 v91, v131, v135, v91
	v_max3_f32 v94, v132, v133, v130
	v_max3_f32 v95, v136, v137, v134
	v_max3_f32 v90, v96, v90, v91
	v_fma_f32 v138, v104, s36, v158
	v_fma_f32 v139, v105, s36, v158
	v_fma_f32 v142, v100, s36, v158
	v_fma_f32 v143, v101, s36, v158
	v_max3_f32 v91, v94, v95, v90
	v_max3_f32 v95, v120, v121, v118
	v_fma_f32 v140, v102, s36, v158
	v_fma_f32 v141, v103, s36, v158
	v_fma_f32 v144, v98, s36, v158
	v_fma_f32 v145, v99, s36, v158
	v_max3_f32 v90, v112, v113, v110
	v_max_f32_e32 v98, v111, v119
	v_max3_f32 v95, v139, v143, v95
	v_max3_f32 v96, v140, v141, v138
	v_max3_f32 v97, v144, v145, v142
	v_max3_f32 v90, v98, v90, v95
	v_max3_f32 v94, v93, v92, v91
	v_max3_f32 v90, v96, v97, v90
	v_max_f32_e32 v94, v94, v90
	s_mov_b32 s23, 0x41000000
	v_cmp_lt_f32_e32 vcc, s23, v94
	s_or_b64 s[50:51], s[42:43], vcc
	v_cndmask_b32_e64 v94, 0, 1, s[50:51]
	v_cmp_ne_u32_e32 vcc, 0, v94
	s_cbranch_vccz .LBB0_893
	v_and_b32_e32 v95, 64, v226
	v_xor_b32_e32 v94, 16, v226
	v_add_u32_e32 v95, 64, v95
	v_cmp_lt_i32_e32 vcc, v94, v95
	s_nop 1
	v_cndmask_b32_e32 v94, v226, v94, vcc
	v_lshlrev_b32_e32 v96, 2, v94
	v_xor_b32_e32 v94, 32, v226
	v_cmp_lt_i32_e32 vcc, v94, v95
	s_nop 1
	v_cndmask_b32_e32 v94, v226, v94, vcc
	v_lshlrev_b32_e32 v97, 2, v94
	ds_bpermute_b32 v94, v96, v93
	v_max_f32_e32 v93, v93, v93
	s_waitcnt lgkmcnt(0)
	v_max_f32_e32 v94, v94, v94
	v_max_f32_e32 v93, v93, v94
	ds_bpermute_b32 v94, v97, v93
	s_waitcnt lgkmcnt(0)
	v_max_f32_e32 v94, v94, v94
	v_max_f32_e32 v93, v93, v94
	v_max_f32_e32 v94, 0, v93
	v_cndmask_b32_e64 v94, v94, v93, s[42:43]
	v_cmp_neq_f32_e32 vcc, s20, v93
	s_nop 1
	v_cndmask_b32_e32 v93, 0, v94, vcc
	v_exp_f32_e64 v94, -v93
	v_sub_f32_e32 v162, v162, v93
	v_sub_f32_e32 v176, v176, v93
	v_sub_f32_e32 v177, v177, v93
	v_sub_f32_e32 v174, v174, v93
	v_sub_f32_e32 v175, v175, v93
	v_sub_f32_e32 v180, v180, v93
	v_sub_f32_e32 v181, v181, v93
	v_sub_f32_e32 v178, v178, v93
	v_sub_f32_e32 v179, v179, v93
	v_sub_f32_e32 v150, v150, v93
	v_sub_f32_e32 v151, v151, v93
	v_sub_f32_e32 v152, v152, v93
	v_sub_f32_e32 v153, v153, v93
	v_sub_f32_e32 v146, v146, v93
	v_sub_f32_e32 v147, v147, v93
	v_sub_f32_e32 v148, v148, v93
	v_sub_f32_e32 v149, v149, v93
	ds_bpermute_b32 v93, v96, v92
	v_max_f32_e32 v92, v92, v92
	v_pk_mul_f32 v[72:73], v[72:73], v[94:95] op_sel_hi:[1,0]
	v_pk_mul_f32 v[70:71], v[70:71], v[94:95] op_sel_hi:[1,0]
	v_pk_mul_f32 v[80:81], v[80:81], v[94:95] op_sel_hi:[1,0]
	s_waitcnt lgkmcnt(0)
	v_max_f32_e32 v93, v93, v93
	v_max_f32_e32 v92, v92, v93
	ds_bpermute_b32 v93, v97, v92
	v_pk_mul_f32 v[78:79], v[78:79], v[94:95] op_sel_hi:[1,0]
	v_pk_mul_f32 v[64:65], v[64:65], v[94:95] op_sel_hi:[1,0]
	v_pk_mul_f32 v[62:63], v[62:63], v[94:95] op_sel_hi:[1,0]
	v_pk_mul_f32 v[76:77], v[76:77], v[94:95] op_sel_hi:[1,0]
	s_waitcnt lgkmcnt(0)
; template <int MODE> ...
;     ...
; #pragma unroll
;         for (int tt = 0; tt < 2; ++tt)
; #pragma unroll
;           for (int hh = 0; hh < 2; ++hh) {
;             float mx = mxq[tt][hh];
;             mx = fmaxf(mx, __shfl_xor(mx, 16));
;             mx = fmaxf(mx, __shfl_xor(mx, 32));
;             const float d = (mx == -INFINITY) ? 0.f : (first ? mx : fmaxf(mx, 0.f));
;             const float alpha = __builtin_amdgcn_exp2f(-d);
;             lsum[tt][hh] *= alpha;
;             nbias[tt][hh] -= d;
; #pragma unroll
;             for (int dt = 0; dt < 4; ++dt)
; #pragma unroll
;               for (int j = 0; j < 4; ++j) O[tt][hh][dt][j] *= alpha;
; #pragma unroll
;             for (int kh = 0; kh < 2; ++kh)
; #pragma unroll
;               for (int t = 0; t < 2; ++t) S[kh][tt][hh][t] = S[kh][tt][hh][t] - d;
;           }
	v_max_f32_e32 v93, v93, v93
	v_max_f32_e32 v92, v92, v93
	v_max_f32_e32 v93, 0, v92
	v_cndmask_b32_e64 v93, v93, v92, s[42:43]
	v_cmp_neq_f32_e32 vcc, s20, v92
	v_pk_mul_f32 v[74:75], v[74:75], v[94:95] op_sel_hi:[1,0]
	s_nop 0
	v_cndmask_b32_e32 v93, 0, v93, vcc
	v_exp_f32_e64 v95, -v93
	v_sub_f32_e32 v164, v164, v93
	v_sub_f32_e32 v184, v184, v93
	v_sub_f32_e32 v185, v185, v93
	v_mov_b32_e32 v92, v95
	v_pk_mul_f32 v[88:89], v[88:89], v[92:93] op_sel_hi:[1,0]
	v_pk_mul_f32 v[86:87], v[86:87], v[92:93] op_sel_hi:[1,0]
	v_pk_mul_f32 v[68:69], v[68:69], v[92:93] op_sel_hi:[1,0]
	v_pk_mul_f32 v[66:67], v[66:67], v[92:93] op_sel_hi:[1,0]
	v_pk_mul_f32 v[60:61], v[60:61], v[92:93] op_sel_hi:[1,0]
	v_pk_mul_f32 v[58:59], v[58:59], v[92:93] op_sel_hi:[1,0]
	v_pk_mul_f32 v[84:85], v[84:85], v[92:93] op_sel_hi:[1,0]
	v_pk_mul_f32 v[82:83], v[82:83], v[92:93] op_sel_hi:[1,0]
	ds_bpermute_b32 v92, v96, v91
	v_max_f32_e32 v91, v91, v91
	v_sub_f32_e32 v182, v182, v93
	v_sub_f32_e32 v183, v183, v93
	v_sub_f32_e32 v188, v188, v93
	s_waitcnt lgkmcnt(0)
	v_max_f32_e32 v92, v92, v92
	v_max_f32_e32 v91, v91, v92
	ds_bpermute_b32 v92, v97, v91
	v_sub_f32_e32 v189, v189, v93
	v_sub_f32_e32 v186, v186, v93
	v_sub_f32_e32 v187, v187, v93
	v_sub_f32_e32 v124, v124, v93
	s_waitcnt lgkmcnt(0)
	v_max_f32_e32 v92, v92, v92
	v_max_f32_e32 v91, v91, v92
	v_max_f32_e32 v92, 0, v91
	v_cndmask_b32_e64 v92, v92, v91, s[42:43]
	v_cmp_neq_f32_e32 vcc, s20, v91
	v_sub_f32_e32 v125, v125, v93
	v_sub_f32_e32 v122, v122, v93
	v_cndmask_b32_e32 v91, 0, v92, vcc
	v_exp_f32_e64 v92, -v91
	v_sub_f32_e32 v160, v160, v91
	v_sub_f32_e32 v114, v114, v91
	v_sub_f32_e32 v115, v115, v91
	v_sub_f32_e32 v116, v116, v91
	v_sub_f32_e32 v117, v117, v91
	v_sub_f32_e32 v106, v106, v91
	v_sub_f32_e32 v107, v107, v91
	v_sub_f32_e32 v108, v108, v91
	v_sub_f32_e32 v109, v109, v91
	v_sub_f32_e32 v132, v132, v91
	v_sub_f32_e32 v133, v133, v91
	v_sub_f32_e32 v130, v130, v91
	v_sub_f32_e32 v131, v131, v91
	v_sub_f32_e32 v136, v136, v91
	v_sub_f32_e32 v137, v137, v91
	v_sub_f32_e32 v134, v134, v91
	v_sub_f32_e32 v135, v135, v91
	ds_bpermute_b32 v91, v96, v90
	v_max_f32_e32 v90, v90, v90
	v_sub_f32_e32 v123, v123, v93
	v_sub_f32_e32 v128, v128, v93
	v_sub_f32_e32 v129, v129, v93
	s_waitcnt lgkmcnt(0)
	v_max_f32_e32 v91, v91, v91
	v_max_f32_e32 v90, v90, v91
	ds_bpermute_b32 v91, v97, v90
	v_sub_f32_e32 v126, v126, v93
	v_sub_f32_e32 v127, v127, v93
	v_pk_mul_f32 v[44:45], v[44:45], v[92:93] op_sel_hi:[1,0]
	v_pk_mul_f32 v[42:43], v[42:43], v[92:93] op_sel_hi:[1,0]
	s_waitcnt lgkmcnt(0)
	v_max_f32_e32 v91, v91, v91
	v_max_f32_e32 v90, v90, v91
	v_max_f32_e32 v91, 0, v90
	v_cndmask_b32_e64 v91, v91, v90, s[42:43]
	v_cmp_neq_f32_e32 vcc, s20, v90
	v_pk_mul_f32 v[36:37], v[36:37], v[92:93] op_sel_hi:[1,0]
	v_pk_mul_f32 v[34:35], v[34:35], v[92:93] op_sel_hi:[1,0]
	v_cndmask_b32_e32 v91, 0, v91, vcc
	v_pk_mul_f32 v[12:13], v[12:13], v[92:93] op_sel_hi:[1,0]
	v_pk_mul_f32 v[10:11], v[10:11], v[92:93] op_sel_hi:[1,0]
	v_pk_mul_f32 v[8:9], v[8:9], v[92:93] op_sel_hi:[1,0]
	v_pk_mul_f32 v[6:7], v[6:7], v[92:93] op_sel_hi:[1,0]
	v_exp_f32_e64 v93, -v91
	v_pk_mul_f32 v[170:171], v[170:171], v[94:95]
	v_sub_f32_e32 v158, v158, v91
	v_sub_f32_e32 v112, v112, v91
	v_mov_b32_e32 v90, v93
	v_pk_mul_f32 v[156:157], v[156:157], v[92:93]
	v_pk_mul_f32 v[48:49], v[48:49], v[90:91] op_sel_hi:[1,0]
	v_pk_mul_f32 v[46:47], v[46:47], v[90:91] op_sel_hi:[1,0]
	v_pk_mul_f32 v[40:41], v[40:41], v[90:91] op_sel_hi:[1,0]
	v_pk_mul_f32 v[38:39], v[38:39], v[90:91] op_sel_hi:[1,0]
	v_pk_mul_f32 v[16:17], v[16:17], v[90:91] op_sel_hi:[1,0]
	v_pk_mul_f32 v[14:15], v[14:15], v[90:91] op_sel_hi:[1,0]
	v_pk_mul_f32 v[4:5], v[4:5], v[90:91] op_sel_hi:[1,0]
	v_pk_mul_f32 v[2:3], v[2:3], v[90:91] op_sel_hi:[1,0]
	v_sub_f32_e32 v113, v113, v91
	v_sub_f32_e32 v110, v110, v91
	v_sub_f32_e32 v111, v111, v91
	v_sub_f32_e32 v120, v120, v91
	v_sub_f32_e32 v121, v121, v91
	v_sub_f32_e32 v118, v118, v91
	v_sub_f32_e32 v119, v119, v91
	v_sub_f32_e32 v140, v140, v91
	v_sub_f32_e32 v141, v141, v91
	v_sub_f32_e32 v138, v138, v91
	v_sub_f32_e32 v139, v139, v91
	v_sub_f32_e32 v144, v144, v91
	v_sub_f32_e32 v145, v145, v91
	v_sub_f32_e32 v142, v142, v91
	v_sub_f32_e32 v143, v143, v91
; #define MFMA(a, b, c) __builtin_amdgcn_mfma_f32_16x16x32_bf16((a), (b), (c), 0, 0, 0)
; template <int MODE> ...
;     ...
; #pragma unroll
;     for (int kh = 0; kh < 2; ++kh) {
; #pragma unroll
;       for (int tt = 0; tt < 2; ++tt) {
;         bf16x8 pf[2];
; #pragma unroll
;         for (int hh = 0; hh < 2; ++hh) {
;           float pv[8];
; #pragma unroll
;           for (int j = 0; j < 4; ++j) {
;             pv[j] = __builtin_amdgcn_exp2f(S[kh][tt][hh][0][j]);
;             pv[4 + j] = __builtin_amdgcn_exp2f(S[kh][tt][hh][1][j]);
;           }
;           lsum[tt][hh] += ((pv[0] + pv[1]) + (pv[2] + pv[3])) + ((pv[4] + pv[5]) + (pv[6] + pv[7]));
;           const uint4 pk = make_uint4(pack2(pv[0], pv[1]), pack2(pv[2], pv[3]), pack2(pv[4], pv[5]), pack2(pv[6], pv[7]));
;           pf[hh] = __builtin_bit_cast(bf16x8, pk);
;         }
; #pragma unroll
;         for (int dt = 0; dt < 4; ++dt) {
;           const bf16x8 vf = *(const bf16x8*)&Vs[(dt * 16 + r) * 64 + (((kh * 4 + g) ^ (r & 7)) * 8)];
;           O[tt][0][dt] = MFMA(vf, pf[0], O[tt][0][dt]);
;           O[tt][1][dt] = MFMA(vf, pf[1], O[tt][1][dt]);
;         }
;       }
;     }
;     }
;     if (more) {
;       u16* Kn = Kbase + ((it + 1) & 1) * (2 * 64 * 64);
;       *(uint4*)&Kn[kwoff] = kr0;
;       *(uint4*)&Kn[64 * 64 + vwoff] = vr0;
;     }
.LBB0_893:
	ds_read_b128 v[102:105], v198 offset:8192
	ds_read_b128 v[98:101], v198 offset:10240
	ds_read_b128 v[94:97], v198 offset:12288
	ds_read_b128 v[90:93], v198 offset:14336
	v_exp_f32_e32 v200, v176
	v_exp_f32_e32 v204, v177
	v_exp_f32_e32 v208, v174
	v_exp_f32_e32 v212, v175
	v_exp_f32_e32 v201, v184
	v_exp_f32_e32 v205, v185
	v_exp_f32_e32 v209, v182
	v_exp_f32_e32 v213, v183
	v_exp_f32_e32 v202, v180
	v_exp_f32_e32 v206, v181
	v_exp_f32_e32 v210, v178
	v_exp_f32_e32 v214, v179
	v_exp_f32_e32 v203, v188
	v_exp_f32_e32 v207, v189
	v_exp_f32_e32 v211, v186
	v_exp_f32_e32 v215, v187
	v_add_f32_e32 v248, v204, v200
	v_add_f32_e32 v249, v205, v201
	v_add_f32_e32 v250, v212, v208
	v_add_f32_e32 v251, v213, v209
	v_add_f32_e32 v248, v250, v248
	v_add_f32_e32 v249, v251, v249
	v_add_f32_e32 v250, v206, v202
	v_add_f32_e32 v251, v207, v203
	v_add_f32_e32 v252, v214, v210
	v_add_f32_e32 v253, v215, v211
	v_add_f32_e32 v250, v252, v250
	v_add_f32_e32 v251, v253, v251
	v_add_f32_e32 v248, v250, v248
	v_add_f32_e32 v249, v251, v249
	v_add_f32_e32 v170, v248, v170
	v_add_f32_e32 v171, v249, v171
	v_cvt_pk_bf16_f32 v240, v200, v204
	v_cvt_pk_bf16_f32 v241, v208, v212
	v_cvt_pk_bf16_f32 v242, v202, v206
	v_cvt_pk_bf16_f32 v243, v210, v214
	v_cvt_pk_bf16_f32 v244, v201, v205
	v_cvt_pk_bf16_f32 v245, v209, v213
	v_cvt_pk_bf16_f32 v246, v203, v207
	v_cvt_pk_bf16_f32 v247, v211, v215
	ds_read_b128 v[200:203], v197 offset:8192
	ds_read_b128 v[204:207], v197 offset:10240
	ds_read_b128 v[208:211], v197 offset:12288
	ds_read_b128 v[212:215], v197 offset:14336
	s_mov_b64 s[42:43], 0
	s_waitcnt lgkmcnt(4)
	v_mfma_f32_16x16x32_bf16 v[70:73], v[102:105], v[240:243], v[70:73]
	v_exp_f32_e32 v176, v114
	v_mfma_f32_16x16x32_bf16 v[78:81], v[98:101], v[240:243], v[78:81]
	v_exp_f32_e32 v182, v115
	v_mfma_f32_16x16x32_bf16 v[62:65], v[94:97], v[240:243], v[62:65]
	v_exp_f32_e32 v178, v107
	v_mfma_f32_16x16x32_bf16 v[74:77], v[90:93], v[240:243], v[74:77]
	v_exp_f32_e32 v184, v116
	v_mfma_f32_16x16x32_bf16 v[86:89], v[102:105], v[244:247], v[86:89]
	v_exp_f32_e32 v180, v108
	v_mfma_f32_16x16x32_bf16 v[66:69], v[98:101], v[244:247], v[66:69]
	v_exp_f32_e32 v188, v117
	v_mfma_f32_16x16x32_bf16 v[58:61], v[94:97], v[244:247], v[58:61]
	v_exp_f32_e32 v186, v109
	v_mfma_f32_16x16x32_bf16 v[82:85], v[90:93], v[244:247], v[82:85]
	v_exp_f32_e32 v175, v120
	v_exp_f32_e32 v183, v113
	v_exp_f32_e32 v179, v121
	v_exp_f32_e32 v189, v111
	v_exp_f32_e32 v187, v119
	v_exp_f32_e32 v174, v106
	v_exp_f32_e32 v177, v112
	v_exp_f32_e32 v185, v110
	v_exp_f32_e32 v181, v118
	v_add_f32_e32 v248, v182, v176
	v_add_f32_e32 v249, v183, v177
	v_add_f32_e32 v250, v188, v184
	v_add_f32_e32 v251, v189, v185
	v_add_f32_e32 v248, v250, v248
	v_add_f32_e32 v249, v251, v249
	v_add_f32_e32 v250, v178, v174
	v_add_f32_e32 v251, v179, v175
	v_add_f32_e32 v252, v186, v180
	v_add_f32_e32 v253, v187, v181
	v_add_f32_e32 v250, v252, v250
	v_add_f32_e32 v251, v253, v251
	v_add_f32_e32 v248, v250, v248
	v_add_f32_e32 v249, v251, v249
	v_add_f32_e32 v156, v248, v156
	v_add_f32_e32 v157, v249, v157
	v_cvt_pk_bf16_f32 v240, v176, v182
	v_cvt_pk_bf16_f32 v241, v184, v188
	v_cvt_pk_bf16_f32 v242, v174, v178
	v_cvt_pk_bf16_f32 v243, v180, v186
	v_cvt_pk_bf16_f32 v244, v177, v183
	v_cvt_pk_bf16_f32 v245, v185, v189
	v_cvt_pk_bf16_f32 v246, v175, v179
	v_cvt_pk_bf16_f32 v247, v181, v187
	v_mfma_f32_16x16x32_bf16 v[6:9], v[90:93], v[240:243], v[6:9]
	v_exp_f32_e32 v108, v150
	v_mfma_f32_16x16x32_bf16 v[42:45], v[102:105], v[240:243], v[42:45]
	v_exp_f32_e32 v114, v151
	v_mfma_f32_16x16x32_bf16 v[34:37], v[98:101], v[240:243], v[34:37]
	v_exp_f32_e32 v116, v152
	v_mfma_f32_16x16x32_bf16 v[10:13], v[94:97], v[240:243], v[10:13]
	v_exp_f32_e32 v120, v153
	v_mfma_f32_16x16x32_bf16 v[2:5], v[90:93], v[244:247], v[2:5]
	v_exp_f32_e32 v109, v124
	v_mfma_f32_16x16x32_bf16 v[46:49], v[102:105], v[244:247], v[46:49]
	v_exp_f32_e32 v107, v128
	v_mfma_f32_16x16x32_bf16 v[38:41], v[98:101], v[244:247], v[38:41]
	v_exp_f32_e32 v115, v125
	v_mfma_f32_16x16x32_bf16 v[14:17], v[94:97], v[244:247], v[14:17]
	v_exp_f32_e32 v111, v129
	s_andn2_b64 vcc, exec, s[48:49]
	s_cbranch_vccnz .Lattn2_nw
	s_and_b32 s98, s2, 0x2000
	s_lshl_b32 s98, s98, 1
	s_add_i32 s98, s98, 32
	v_lshl_add_u32 v235, v165, 1, s98
	v_lshl_add_u32 v238, v190, 1, s98
	s_waitcnt vmcnt(1)
	ds_write_b128 v235, v[50:53]
	s_waitcnt vmcnt(0)
	ds_write_b128 v238, v[54:57] offset:8192
; #define MFMA(a, b, c) __builtin_amdgcn_mfma_f32_16x16x32_bf16((a), (b), (c), 0, 0, 0)
; template <int MODE> ...
;     ...
; #pragma unroll
;     for (int kh = 0; kh < 2; ++kh) {
; #pragma unroll
;       for (int tt = 0; tt < 2; ++tt) {
;         bf16x8 pf[2];
; #pragma unroll
;         for (int hh = 0; hh < 2; ++hh) {
;           float pv[8];
; #pragma unroll
;           for (int j = 0; j < 4; ++j) {
;             pv[j] = __builtin_amdgcn_exp2f(S[kh][tt][hh][0][j]);
;             pv[4 + j] = __builtin_amdgcn_exp2f(S[kh][tt][hh][1][j]);
;           }
;           lsum[tt][hh] += ((pv[0] + pv[1]) + (pv[2] + pv[3])) + ((pv[4] + pv[5]) + (pv[6] + pv[7]));
;           const uint4 pk = make_uint4(pack2(pv[0], pv[1]), pack2(pv[2], pv[3]), pack2(pv[4], pv[5]), pack2(pv[6], pv[7]));
;           pf[hh] = __builtin_bit_cast(bf16x8, pk);
;         }
; #pragma unroll
;         for (int dt = 0; dt < 4; ++dt) {
;           const bf16x8 vf = *(const bf16x8*)&Vs[(dt * 16 + r) * 64 + (((kh * 4 + g) ^ (r & 7)) * 8)];
;           O[tt][0][dt] = MFMA(vf, pf[0], O[tt][0][dt]);
;           O[tt][1][dt] = MFMA(vf, pf[1], O[tt][1][dt]);
;         }
;       }
;     }
.Lattn2_nw:
	v_exp_f32_e32 v117, v122
	v_exp_f32_e32 v113, v126
	v_exp_f32_e32 v121, v123
	v_exp_f32_e32 v119, v127
	v_exp_f32_e32 v106, v146
	v_exp_f32_e32 v110, v147
	v_exp_f32_e32 v112, v148
	v_exp_f32_e32 v118, v149
	v_add_f32_e32 v248, v114, v108
	v_add_f32_e32 v249, v115, v109
	v_add_f32_e32 v250, v120, v116
	v_add_f32_e32 v251, v121, v117
	v_add_f32_e32 v248, v250, v248
	v_add_f32_e32 v249, v251, v249
	v_add_f32_e32 v250, v110, v106
	v_add_f32_e32 v251, v111, v107
	v_add_f32_e32 v252, v118, v112
	v_add_f32_e32 v253, v119, v113
	v_add_f32_e32 v250, v252, v250
	v_add_f32_e32 v251, v253, v251
	v_add_f32_e32 v248, v250, v248
	v_add_f32_e32 v249, v251, v249
	v_add_f32_e32 v170, v248, v170
	v_add_f32_e32 v171, v249, v171
	v_cvt_pk_bf16_f32 v240, v108, v114
	v_cvt_pk_bf16_f32 v241, v116, v120
	v_cvt_pk_bf16_f32 v242, v106, v110
	v_cvt_pk_bf16_f32 v243, v112, v118
	v_cvt_pk_bf16_f32 v244, v109, v115
	v_cvt_pk_bf16_f32 v245, v117, v121
	v_cvt_pk_bf16_f32 v246, v107, v111
	v_cvt_pk_bf16_f32 v247, v113, v119
	s_waitcnt lgkmcnt(0)
	v_mfma_f32_16x16x32_bf16 v[70:73], v[200:203], v[240:243], v[70:73]
	v_exp_f32_e32 v130, v130
	v_mfma_f32_16x16x32_bf16 v[78:81], v[204:207], v[240:243], v[78:81]
	v_exp_f32_e32 v128, v134
	v_mfma_f32_16x16x32_bf16 v[62:65], v[208:211], v[240:243], v[62:65]
	v_exp_f32_e32 v134, v135
	v_mfma_f32_16x16x32_bf16 v[74:77], v[212:215], v[240:243], v[74:77]
	v_exp_f32_e32 v127, v145
	v_mfma_f32_16x16x32_bf16 v[86:89], v[200:203], v[244:247], v[86:89]
	v_exp_f32_e32 v123, v144
	v_mfma_f32_16x16x32_bf16 v[66:69], v[204:207], v[244:247], v[66:69]
	v_exp_f32_e32 v129, v142
	v_mfma_f32_16x16x32_bf16 v[58:61], v[208:211], v[244:247], v[58:61]
	v_exp_f32_e32 v135, v143
	v_mfma_f32_16x16x32_bf16 v[82:85], v[212:215], v[244:247], v[82:85]
	v_exp_f32_e32 v124, v132
	v_exp_f32_e32 v122, v136
	v_exp_f32_e32 v132, v133
	v_exp_f32_e32 v126, v137
	v_exp_f32_e32 v136, v131
	v_exp_f32_e32 v125, v140
	v_exp_f32_e32 v133, v141
	v_exp_f32_e32 v131, v138
	v_exp_f32_e32 v137, v139
	v_add_f32_e32 v248, v132, v124
	v_add_f32_e32 v249, v133, v125
	v_add_f32_e32 v250, v136, v130
	v_add_f32_e32 v251, v137, v131
	v_add_f32_e32 v248, v250, v248
	v_add_f32_e32 v249, v251, v249
	v_add_f32_e32 v250, v126, v122
	v_add_f32_e32 v251, v127, v123
	v_add_f32_e32 v252, v134, v128
	v_add_f32_e32 v253, v135, v129
	v_add_f32_e32 v250, v252, v250
	v_add_f32_e32 v251, v253, v251
	v_add_f32_e32 v248, v250, v248
	v_add_f32_e32 v249, v251, v249
	v_add_f32_e32 v156, v248, v156
	v_add_f32_e32 v157, v249, v157
	v_cvt_pk_bf16_f32 v240, v124, v132
	v_cvt_pk_bf16_f32 v241, v130, v136
	v_cvt_pk_bf16_f32 v242, v122, v126
	v_cvt_pk_bf16_f32 v243, v128, v134
	v_cvt_pk_bf16_f32 v244, v125, v133
	v_cvt_pk_bf16_f32 v245, v131, v137
	v_cvt_pk_bf16_f32 v246, v123, v127
	v_cvt_pk_bf16_f32 v247, v129, v135
	v_mfma_f32_16x16x32_bf16 v[42:45], v[200:203], v[240:243], v[42:45]
	v_mfma_f32_16x16x32_bf16 v[34:37], v[204:207], v[240:243], v[34:37]
	v_mfma_f32_16x16x32_bf16 v[10:13], v[208:211], v[240:243], v[10:13]
	v_mfma_f32_16x16x32_bf16 v[6:9], v[212:215], v[240:243], v[6:9]
	v_mfma_f32_16x16x32_bf16 v[46:49], v[200:203], v[244:247], v[46:49]
	v_mfma_f32_16x16x32_bf16 v[38:41], v[204:207], v[244:247], v[38:41]
	v_mfma_f32_16x16x32_bf16 v[14:17], v[208:211], v[244:247], v[14:17]
	v_mfma_f32_16x16x32_bf16 v[2:5], v[212:215], v[244:247], v[2:5]
	s_andn2_b64 vcc, exec, s[48:49]
	s_cbranch_vccz .Lattn2_adv
